# norm1: per-row residual source pointer selected from preloaded registers instead of a dependent load; store-drain wait removed
# speedup vs baseline: 1.1001x; 1.0008x over previous
; __device__ __forceinline__ int opaque_tid() { int t = threadIdx.x; asm volatile("" : "+v"(t)); return t; }
; #define layer launder_s(layer_)
; __device__ __forceinline__ const float* resid_src(const Params& p, int layer, int which, int row) {
;   if (layer == 0 && which == 0) return row < TL ? p.in[0] + (size_t)row * D : p.in[2] + (size_t)(row - TL) * D;
;   return (const float*)(p.ws + O_XRES) + (size_t)row * D;
; }
; __device__ __forceinline__ void norm_item(const Params& p, int layer, int which, int item) {
;   int tid = opaque_tid(), wave = tid >> 6, lane = tid & 63;
;   const float* MOD = (const float*)(p.ws + O_MOD);
;   const float* g = p.in[which == 0 ? 6 : 7] + layer * D;
;   u16* XN = (u16*)(p.ws + O_XN);
;   for (int i = 0; i < 9; i++) {
;     int row = item * 72 + wave * 9 + i;
;     const float* src = resid_src(p, layer, which, row);
;     int m = row < TL ? (row >> 11) : 8;
;     const float* md = MOD + (size_t)(layer * 9 + m) * 6144 + (which == 0 ? 0 : 3072);
;     float4 v[4];
;     float ss = 0.f;
; #pragma unroll
;     for (int q = 0; q < 4; q++) {
;       v[q] = *(const float4*)(src + q * 256 + lane * 4);
.LBB0_159:
	s_mov_b64 s[6:7], s[50:51]
	v_readlane_b32 s12, v255, 13
	v_mov_b32_e32 v6, v228
	s_waitcnt vmcnt(0)
	v_mov_b64_e32 v[0:1], s[6:7]
	v_mov_b64_e32 v[2:3], s[6:7]
	global_load_dwordx2 v[0:1], v[0:1], off offset:336
	s_nop 0
	global_load_dwordx2 v[2:3], v[2:3], off offset:48
	v_cmp_lt_i32_e32 vcc, v236, v235
	s_add_u32 s8, s6, 0x150
	s_addc_u32 s9, s7, 0
	v_cndmask_b32_e32 v8, v234, v236, vcc
	v_cmp_lt_i32_e32 vcc, v237, v235
	v_lshlrev_b32_e32 v20, 2, v8
	v_ashrrev_i32_e32 v8, 6, v6
	v_cndmask_b32_e32 v9, v234, v237, vcc
	v_cmp_lt_i32_e32 vcc, v238, v235
	v_lshlrev_b32_e32 v6, 2, v6
	s_lshl_b32 s4, s12, 10
	v_cndmask_b32_e32 v10, v234, v238, vcc
	v_cmp_lt_i32_e32 vcc, v239, v235
	v_and_b32_e32 v16, 0xfc, v6
	s_ashr_i32 s5, s4, 31
	v_cndmask_b32_e32 v11, v234, v239, vcc
	v_cmp_lt_i32_e32 vcc, v240, v235
	v_mov_b32_e32 v4, s16
	v_mov_b32_e32 v5, v161
	v_cndmask_b32_e32 v12, v234, v240, vcc
	v_cmp_lt_i32_e32 vcc, v241, v235
	v_lshlrev_b32_e32 v160, 2, v16
	v_lshlrev_b32_e32 v21, 2, v9
	v_cndmask_b32_e32 v13, v234, v241, vcc
	v_mad_u64_u32 v[8:9], s[10:11], v8, 9, v[4:5]
	s_cmp_lg_u32 s12, 0
	s_mov_b64 s[14:15], 0x6c00000
	v_lshlrev_b32_e32 v22, 2, v10
	v_lshlrev_b32_e32 v24, 2, v12
	v_lshlrev_b32_e32 v25, 2, v13
	s_mul_i32 s19, s12, 9
	v_or_b32_e32 v18, 0x100, v16
	v_or_b32_e32 v6, 0x200, v16
	v_or_b32_e32 v10, 0x300, v16
	s_cselect_b64 s[10:11], -1, 0
	s_add_u32 s12, s6, 16
	s_mov_b32 s18, 0
	v_mov_b32_e32 v7, v161
	v_lshlrev_b32_e32 v23, 2, v11
	v_lshlrev_b32_e32 v4, 2, v16
	v_lshlrev_b32_e32 v6, 2, v6
	v_lshlrev_b32_e32 v10, 2, v10
	s_addc_u32 s13, s7, 0
	v_mov_b32_e32 v11, v161
	s_waitcnt vmcnt(0) lgkmcnt(0)
	v_lshl_add_u64 v[12:13], v[0:1], 0, s[14:15]
	v_lshl_add_u64 v[2:3], s[4:5], 2, v[2:3]
	v_lshl_add_u64 v[14:15], v[2:3], 0, v[160:161]
	v_lshlrev_b32_e32 v160, 1, v16
	v_lshl_add_u64 v[0:1], v[0:1], 0, v[160:161]
	s_mov_b64 s[4:5], 0x4800000
	v_lshlrev_b32_e32 v160, 2, v18
	v_lshl_add_u64 v[16:17], v[0:1], 0, s[4:5]
	v_mov_b64_e32 v[132:133], s[6:7]
	global_load_dwordx2 v[124:125], v[132:133], off
	global_load_dwordx2 v[126:127], v[132:133], off offset:16
	global_load_dwordx2 v[130:131], v[132:133], off offset:336
	s_waitcnt vmcnt(0)
	s_branch .LBB0_162

; __device__ __forceinline__ unsigned pack2(float a, float b) { unsigned r; asm("v_cvt_pk_bf16_f32 %0, %1, %2" : "=v"(r) : "v"(a), "v"(b)); return r; }
; #define layer launder_s(layer_)
; __device__ __forceinline__ const float* resid_src(const Params& p, int layer, int which, int row) {
;   if (layer == 0 && which == 0) return row < TL ? p.in[0] + (size_t)row * D : p.in[2] + (size_t)(row - TL) * D;
;   return (const float*)(p.ws + O_XRES) + (size_t)row * D;
; __device__ __forceinline__ void norm_item(const Params& p, int layer, int which, int item) {
;     ...
;   for (int i = 0; i < 9; i++) {
;     int row = item * 72 + wave * 9 + i;
;     const float* src = resid_src(p, layer, which, row);
;     int m = row < TL ? (row >> 11) : 8;
;     const float* md = MOD + (size_t)(layer * 9 + m) * 6144 + (which == 0 ? 0 : 3072);
;     float4 v[4];
;     float ss = 0.f;
; #pragma unroll
;     for (int q = 0; q < 4; q++) {
;       v[q] = *(const float4*)(src + q * 256 + lane * 4);
;       ss += v[q].x * v[q].x + v[q].y * v[q].y + v[q].z * v[q].z + v[q].w * v[q].w;
;     }
;     ss = wave_sum(ss);
;     float rstd = rsqrtf(ss * (1.0f / 1024.0f) + EPS);
; #pragma unroll
;     for (int q = 0; q < 4; q++) {
;       int cidx = q * 256 + lane * 4;
;       float4 gg = *(const float4*)(g + cidx);
;       float4 sh = *(const float4*)(md + cidx);
;       float4 sc = *(const float4*)(md + 1024 + cidx);
;       float o0 = v[q].x * rstd * gg.x * (1.f + sc.x) + sh.x;
;       float o1 = v[q].y * rstd * gg.y * (1.f + sc.y) + sh.y;
;       float o2 = v[q].z * rstd * gg.z * (1.f + sc.z) + sh.z;
;       float o3 = v[q].w * rstd * gg.w * (1.f + sc.w) + sh.w;
;       uint2 o; o.x = pack2(o0, o1); o.y = pack2(o2, o3);
;       *(uint2*)(XN + (size_t)row * D + cidx) = o;
;     }
;   }
.LBB0_161:
	v_cmp_eq_u32_e32 vcc, s8, v2
	v_cmp_eq_u32_e64 s[14:15], s12, v2
	s_nop 1
	v_cndmask_b32_e64 v3, v125, v127, s[14:15]
	v_cndmask_b32_e64 v2, v124, v126, s[14:15]
	v_cndmask_b32_e32 v3, v3, v131, vcc
	v_cndmask_b32_e32 v2, v2, v130, vcc
	v_lshlrev_b64 v[0:1], 12, v[0:1]
	v_min_i32_e32 v9, 0x4000, v18
	v_ashrrev_i32_e32 v9, 11, v9
	v_add_u32_e32 v9, s19, v9
	s_movk_i32 s4, 0x6000
	v_mad_i64_i32 v[46:47], s[4:5], v9, s4, v[12:13]
	s_mov_b64 s[4:5], 0x1000
	s_nop 0
	v_lshl_add_u64 v[50:51], v[46:47], 0, s[4:5]
	v_lshl_add_u64 v[38:39], v[50:51], 0, v[4:5]
	v_lshl_add_u64 v[120:121], v[50:51], 0, v[4:5]
	v_lshl_add_u64 v[52:53], v[46:47], 0, v[4:5]
	v_lshlrev_b64 v[18:19], 11, v[18:19]
	v_lshl_add_u64 v[18:19], v[16:17], 0, v[18:19]
	s_add_i32 s18, s18, 1
	s_cmp_lg_u32 s18, 9
	s_waitcnt lgkmcnt(0)
	v_lshl_add_u64 v[0:1], v[2:3], 0, v[0:1]
	v_lshl_add_u64 v[0:1], v[0:1], 0, v[4:5]
	global_load_dwordx4 v[26:29], v[0:1], off
	global_load_dwordx4 v[30:33], v[0:1], off offset:1024
	global_load_dwordx4 v[34:37], v[0:1], off offset:2048
	s_nop 0
	global_load_dwordx4 v[0:3], v[0:1], off offset:3072
	s_nop 0
	global_load_dwordx4 v[38:41], v[38:39], off
	s_nop 0
	global_load_dwordx4 v[42:45], v[14:15], off
	global_load_dwordx4 v[46:49], v[52:53], off
	global_load_dwordx4 v[84:87], v[14:15], off offset:1024
	global_load_dwordx4 v[88:91], v[120:121], off offset:1024
	global_load_dwordx4 v[92:95], v[52:53], off offset:1024
	global_load_dwordx4 v[96:99], v[14:15], off offset:2048
	global_load_dwordx4 v[100:103], v[120:121], off offset:2048
	global_load_dwordx4 v[104:107], v[52:53], off offset:2048
	global_load_dwordx4 v[108:111], v[14:15], off offset:3072
	global_load_dwordx4 v[112:115], v[120:121], off offset:3072
	global_load_dwordx4 v[116:119], v[52:53], off offset:3072
	s_waitcnt vmcnt(0) lgkmcnt(0)
	v_mov_b32_e32 v56, v27
	v_mov_b32_e32 v57, v31
	v_mov_b32_e32 v54, v26
	v_mov_b32_e32 v55, v30
	v_mov_b32_e32 v64, v35
	v_mov_b32_e32 v65, v1
	v_pk_mul_f32 v[56:57], v[56:57], v[56:57]
	v_mov_b32_e32 v58, v28
	v_mov_b32_e32 v59, v32
	v_mov_b32_e32 v62, v34
	v_mov_b32_e32 v63, v0
	v_pk_mul_f32 v[64:65], v[64:65], v[64:65]
	v_pk_fma_f32 v[54:55], v[54:55], v[54:55], v[56:57]
	v_mov_b32_e32 v60, v29
	v_mov_b32_e32 v61, v33
	v_mov_b32_e32 v66, v36
	v_mov_b32_e32 v67, v2
	v_pk_fma_f32 v[56:57], v[62:63], v[62:63], v[64:65]
	v_pk_fma_f32 v[54:55], v[58:59], v[58:59], v[54:55]
	v_mov_b32_e32 v68, v37
	v_mov_b32_e32 v69, v3
	v_pk_fma_f32 v[56:57], v[66:67], v[66:67], v[56:57]
	v_pk_fma_f32 v[54:55], v[60:61], v[60:61], v[54:55]
	v_pk_fma_f32 v[56:57], v[68:69], v[68:69], v[56:57]
	v_add_f32_e32 v9, v54, v55
	v_add_f32_e32 v9, v9, v56
	v_add_f32_e32 v9, v9, v57
	ds_bpermute_b32 v54, v20, v9
	v_add_f32_e32 v38, 1.0, v38
	v_add_f32_e32 v39, 1.0, v39
	v_add_f32_e32 v40, 1.0, v40
	v_add_f32_e32 v41, 1.0, v41
	s_waitcnt lgkmcnt(0)
	v_add_f32_e32 v9, v9, v54
	ds_bpermute_b32 v54, v21, v9
	s_waitcnt lgkmcnt(0)
	v_add_f32_e32 v9, v9, v54
	ds_bpermute_b32 v54, v22, v9
	s_waitcnt lgkmcnt(0)
	v_add_f32_e32 v9, v9, v54
	ds_bpermute_b32 v54, v23, v9
	s_waitcnt lgkmcnt(0)
	v_add_f32_e32 v9, v9, v54
	ds_bpermute_b32 v54, v24, v9
	s_waitcnt lgkmcnt(0)
	v_add_f32_e32 v9, v9, v54
	ds_bpermute_b32 v56, v25, v9
	v_lshl_add_u64 v[54:55], v[50:51], 0, v[160:161]
	s_waitcnt lgkmcnt(0)
	v_add_f32_e32 v9, v9, v56
	v_fmamk_f32 v9, v9, 0x3a800000, v229
	v_mul_f32_e32 v56, 0x4b800000, v9
	v_cmp_gt_f32_e32 vcc, s89, v9
	s_nop 1
	v_cndmask_b32_e32 v9, v9, v56, vcc
	v_rsq_f32_e32 v9, v9
	s_nop 0
	v_mul_f32_e32 v56, 0x45800000, v9
	v_cndmask_b32_e32 v9, v9, v56, vcc
	v_mul_f32_e32 v26, v26, v9
	v_mul_f32_e32 v27, v27, v9
	v_mul_f32_e32 v28, v28, v9
	v_mul_f32_e32 v29, v29, v9
	v_mul_f32_e32 v26, v42, v26
	v_mul_f32_e32 v27, v43, v27
	v_mul_f32_e32 v28, v44, v28
	v_mul_f32_e32 v29, v45, v29
	v_fma_f32 v26, v38, v26, v46
	v_fma_f32 v27, v39, v27, v47
	v_fma_f32 v28, v40, v28, v48
	v_fmac_f32_e32 v49, v29, v41
	v_cvt_pk_bf16_f32 v26, v26, v27
	v_cvt_pk_bf16_f32 v27, v28, v49
	global_store_dwordx2 v[18:19], v[26:27], off
	v_mov_b32_e32 v26, v84
	v_mov_b32_e32 v27, v85
	v_mov_b32_e32 v28, v86
	v_mov_b32_e32 v29, v87
	s_nop 0
	v_mov_b32_e32 v38, v88
	v_mov_b32_e32 v39, v89
	v_mov_b32_e32 v40, v90
	v_mov_b32_e32 v41, v91
	v_mov_b32_e32 v42, v92
	v_mov_b32_e32 v43, v93
	v_mov_b32_e32 v44, v94
	v_mov_b32_e32 v45, v95
	v_mul_f32_e32 v30, v30, v9
	v_mul_f32_e32 v31, v31, v9
	v_mul_f32_e32 v32, v32, v9
	v_mul_f32_e32 v33, v33, v9
	v_lshl_add_u64 v[46:47], v[50:51], 0, v[6:7]
	v_mul_f32_e32 v34, v34, v9
	v_mul_f32_e32 v35, v35, v9
	v_mul_f32_e32 v36, v36, v9
	v_mul_f32_e32 v37, v37, v9
	v_mul_f32_e32 v0, v0, v9
	v_mul_f32_e32 v1, v1, v9
	v_mul_f32_e32 v2, v2, v9
	v_mul_f32_e32 v3, v3, v9
	s_waitcnt lgkmcnt(0)
	v_mul_f32_e32 v26, v30, v26
	v_add_f32_e32 v30, 1.0, v38
	v_mul_f32_e32 v27, v31, v27
	v_add_f32_e32 v31, 1.0, v39
	v_mul_f32_e32 v28, v32, v28
	v_add_f32_e32 v32, 1.0, v40
	v_mul_f32_e32 v29, v33, v29
	v_add_f32_e32 v33, 1.0, v41
	v_fma_f32 v26, v26, v30, v42
	v_fma_f32 v27, v27, v31, v43
	v_fma_f32 v28, v28, v32, v44
	v_fmac_f32_e32 v45, v29, v33
	v_cvt_pk_bf16_f32 v26, v26, v27
	v_cvt_pk_bf16_f32 v27, v28, v45
	global_store_dwordx2 v[18:19], v[26:27], off offset:512
	v_mov_b32_e32 v26, v96
	v_mov_b32_e32 v27, v97
	v_mov_b32_e32 v28, v98
	v_mov_b32_e32 v29, v99
	s_nop 0
	v_mov_b32_e32 v30, v100
	v_mov_b32_e32 v31, v101
	v_mov_b32_e32 v32, v102
	v_mov_b32_e32 v33, v103
	v_mov_b32_e32 v38, v104
	v_mov_b32_e32 v39, v105
	v_mov_b32_e32 v40, v106
	v_mov_b32_e32 v41, v107
	v_lshl_add_u64 v[42:43], v[50:51], 0, v[10:11]
	s_waitcnt lgkmcnt(0)
	v_mul_f32_e32 v26, v34, v26
	v_add_f32_e32 v30, 1.0, v30
	v_mul_f32_e32 v27, v35, v27
	v_add_f32_e32 v31, 1.0, v31
	v_mul_f32_e32 v28, v36, v28
	v_add_f32_e32 v32, 1.0, v32
	v_mul_f32_e32 v29, v37, v29
	v_add_f32_e32 v33, 1.0, v33
	v_fma_f32 v26, v26, v30, v38
	v_fma_f32 v27, v27, v31, v39
	v_fma_f32 v28, v28, v32, v40
	v_fmac_f32_e32 v41, v29, v33
	v_cvt_pk_bf16_f32 v26, v26, v27
	v_cvt_pk_bf16_f32 v27, v28, v41
	global_store_dwordx2 v[18:19], v[26:27], off offset:1024
	v_mov_b32_e32 v26, v108
	v_mov_b32_e32 v27, v109
	v_mov_b32_e32 v28, v110
	v_mov_b32_e32 v29, v111
	s_nop 0
	v_mov_b32_e32 v30, v112
	v_mov_b32_e32 v31, v113
	v_mov_b32_e32 v32, v114
	v_mov_b32_e32 v33, v115
	v_mov_b32_e32 v34, v116
	v_mov_b32_e32 v35, v117
	v_mov_b32_e32 v36, v118
	v_mov_b32_e32 v37, v119
	s_waitcnt lgkmcnt(0)
	v_mul_f32_e32 v0, v0, v26
	v_add_f32_e32 v9, 1.0, v30
	v_mul_f32_e32 v1, v1, v27
	v_add_f32_e32 v26, 1.0, v31
	v_mul_f32_e32 v2, v2, v28
	v_add_f32_e32 v27, 1.0, v32
	v_mul_f32_e32 v3, v3, v29
	v_add_f32_e32 v28, 1.0, v33
	v_fma_f32 v0, v0, v9, v34
	v_fma_f32 v1, v1, v26, v35
	v_fma_f32 v2, v2, v27, v36
	v_fmac_f32_e32 v37, v3, v28
	v_cvt_pk_bf16_f32 v0, v0, v1
	v_cvt_pk_bf16_f32 v1, v2, v37
	global_store_dwordx2 v[18:19], v[0:1], off offset:1536
	s_cbranch_scc0 .LBB0_158
